# second (mid-way) background write-back at the mixing-phase barriers
# baseline (speedup 1.0000x reference)
; __device__ __forceinline__ void fast_grid_barrier(unsigned* base, int seam, int tid) {
;     asm volatile("s_waitcnt vmcnt(0)" ::: "memory");
;     __syncthreads();
;     if (tid == 0) {
;         unsigned* cnt = base + seam * 128;
;         unsigned* flg = cnt + 64;
;         __builtin_amdgcn_fence(__ATOMIC_RELEASE, "agent");
;         asm volatile("s_waitcnt vmcnt(0)" ::: "memory");
;         const unsigned old = __hip_atomic_fetch_add(cnt, 1u, __ATOMIC_RELAXED, __HIP_MEMORY_SCOPE_AGENT);
;         if (old == gridDim.x - 1) __hip_atomic_store(flg, 1u, __ATOMIC_RELAXED, __HIP_MEMORY_SCOPE_AGENT);
;         else { unsigned sp = 0; while (__hip_atomic_load(flg, __ATOMIC_RELAXED, __HIP_MEMORY_SCOPE_AGENT) == 0u) { __builtin_amdgcn_s_sleep(2); if (++sp > (1u << 22)) break; } }
;         __builtin_amdgcn_fence(__ATOMIC_ACQUIRE, "agent");
;         asm volatile("s_waitcnt vmcnt(0)" ::: "memory");
;     }
;     __syncthreads();
; }
.Lsm3_early:
	s_mul_i32 s3, s99, 2
	v_cmp_eq_u32_e32 vcc, s3, v1
	s_cbranch_vccnz .Lsm3_ewb
	s_lshr_b32 s5, s99, 1
	s_add_i32 s3, s3, s5
	v_cmp_eq_u32_e32 vcc, s3, v1
	s_cbranch_vccnz .Lsm3_ewb
	s_branch .Lsm3_wtop
.Lsm3_ewb:
	buffer_wbl2 sc1

; __device__ __forceinline__ void fast_grid_barrier(unsigned* base, int seam, int tid) {
;     asm volatile("s_waitcnt vmcnt(0)" ::: "memory");
;     __syncthreads();
;     if (tid == 0) {
;         unsigned* cnt = base + seam * 128;
;         unsigned* flg = cnt + 64;
;         __builtin_amdgcn_fence(__ATOMIC_RELEASE, "agent");
;         asm volatile("s_waitcnt vmcnt(0)" ::: "memory");
;         const unsigned old = __hip_atomic_fetch_add(cnt, 1u, __ATOMIC_RELAXED, __HIP_MEMORY_SCOPE_AGENT);
;         if (old == gridDim.x - 1) __hip_atomic_store(flg, 1u, __ATOMIC_RELAXED, __HIP_MEMORY_SCOPE_AGENT);
;         else { unsigned sp = 0; while (__hip_atomic_load(flg, __ATOMIC_RELAXED, __HIP_MEMORY_SCOPE_AGENT) == 0u) { __builtin_amdgcn_s_sleep(2); if (++sp > (1u << 22)) break; } }
;         __builtin_amdgcn_fence(__ATOMIC_ACQUIRE, "agent");
;         asm volatile("s_waitcnt vmcnt(0)" ::: "memory");
;     }
;     __syncthreads();
; }
.Lsm7_early:
	s_mul_i32 s3, s99, 6
	v_cmp_eq_u32_e32 vcc, s3, v1
	s_cbranch_vccnz .Lsm7_ewb
	s_lshr_b32 s5, s99, 1
	s_add_i32 s3, s3, s5
	v_cmp_eq_u32_e32 vcc, s3, v1
	s_cbranch_vccnz .Lsm7_ewb
	s_branch .Lsm7_wtop
